# phase-0 weight-copy tile loop: the loop-head vmcnt(0) (which only waited for the previous tile's two stores) relaxed to vmcnt(2), first-tile wait moved to the preheader; on top of the modulation defer
# speedup vs baseline: 1.0002x; 1.0002x over previous
.LBB0_733:
	v_mov_b32 v0, 0
	s_movk_i32 s26, 0x1a0
	v_add_u32_sdwa v2, v0, v160 dst_sel:DWORD dst_unused:UNUSED_PAD src0_sel:DWORD src1_sel:BYTE_0
	v_ashrrev_i32_e32 v0, 4, v2
	v_lshl_add_u32 v10, s22, 6, v0
	v_add_u32_e32 v0, 48, v10
	v_add_u32_e32 v8, 16, v10
	v_ashrrev_i32_e32 v1, 31, v0
	v_lshlrev_b32_e32 v2, 4, v2
	v_ashrrev_i32_e32 v9, 31, v8
	v_mul_lo_u32 v3, s6, v1
	v_mul_lo_u32 v4, s7, v0
	v_mad_u64_u32 v[0:1], s[8:9], s6, v0, 0
	v_and_b32_e32 v128, 0xf0, v2
	v_add_u32_e32 v2, 32, v10
	v_mul_lo_u32 v11, s6, v9
	v_mul_lo_u32 v12, s7, v8
	v_mad_u64_u32 v[8:9], s[12:13], s6, v8, 0
	v_add3_u32 v1, v1, v3, v4
	v_ashrrev_i32_e32 v3, 31, v2
	v_add3_u32 v9, v9, v11, v12
	v_ashrrev_i32_e32 v11, 31, v10
	s_lshl_b32 s8, s23, 6
	v_mul_lo_u32 v4, s6, v3
	v_mul_lo_u32 v5, s7, v2
	v_mad_u64_u32 v[2:3], s[12:13], s6, v2, 0
	v_mul_lo_u32 v12, s6, v11
	v_mul_lo_u32 v13, s7, v10
	v_mad_u64_u32 v[10:11], s[6:7], s6, v10, 0
	s_ashr_i32 s9, s8, 31
	v_add3_u32 v3, v3, v4, v5
	v_add3_u32 v11, v11, v12, v13
	v_lshl_add_u64 v[0:1], v[0:1], 2, s[4:5]
	s_lshl_b64 s[8:9], s[8:9], 2
	v_lshl_add_u64 v[2:3], v[2:3], 2, s[4:5]
	v_lshl_add_u64 v[8:9], v[8:9], 2, s[4:5]
	v_lshl_add_u64 v[10:11], v[10:11], 2, s[4:5]
	v_lshl_add_u64 v[0:1], v[0:1], 0, s[8:9]
	v_lshl_add_u64 v[2:3], v[2:3], 0, s[8:9]
	v_lshl_add_u64 v[8:9], v[8:9], 0, s[8:9]
	v_lshl_add_u64 v[10:11], v[10:11], 0, s[8:9]
	v_lshl_add_u64 v[0:1], v[0:1], 0, v[128:129]
	v_lshl_add_u64 v[4:5], v[2:3], 0, v[128:129]
	v_lshl_add_u64 v[8:9], v[8:9], 0, v[128:129]
	v_lshl_add_u64 v[12:13], v[10:11], 0, v[128:129]
	global_load_dwordx4 v[0:3], v[0:1], off nt
	s_nop 0
	global_load_dwordx4 v[4:7], v[4:5], off nt
	s_nop 0
	global_load_dwordx4 v[8:11], v[8:9], off nt
	s_nop 0
	global_load_dwordx4 v[12:15], v[12:13], off nt
	s_lshl_b32 s4, s10, 16
	s_add_i32 s25, s4, 0
	s_add_u32 s4, s84, 0x4600000
	s_addc_u32 s5, s85, 0
	s_add_u32 s6, s84, 0x2600000
	s_addc_u32 s7, s85, 0
	s_add_u32 s8, s84, 0x1e00000
	s_addc_u32 s9, s85, 0
	s_mov_b32 s28, s23
	s_mov_b32 s27, s22
	s_mov_b32 s29, s24
	s_mov_b64 s[12:13], s[0:1]
	s_waitcnt vmcnt(0)
	s_branch .LBB0_737

.LBB0_737:
	s_add_i32 s21, s21, s26
	s_cmpk_gt_i32 s21, 0xc9f
	s_cselect_b64 s[10:11], -1, 0
	s_and_b64 vcc, exec, s[10:11]
	s_waitcnt vmcnt(2)
	v_mov_b32_e32 v31, v3
	v_mov_b32_e32 v30, v2
	v_mov_b32_e32 v29, v1
	v_mov_b32_e32 v28, v0
	v_mov_b32_e32 v27, v7
	v_mov_b32_e32 v26, v6
	v_mov_b32_e32 v25, v5
	v_mov_b32_e32 v24, v4
	v_mov_b32_e32 v23, v11
	v_mov_b32_e32 v22, v10
	v_mov_b32_e32 v21, v9
	v_mov_b32_e32 v20, v8
	v_mov_b32_e32 v19, v15
	v_mov_b32_e32 v18, v14
	v_mov_b32_e32 v17, v13
	v_mov_b32_e32 v16, v12
	s_cbranch_vccnz .LBB0_736
	s_cmpk_gt_i32 s21, 0x39f
	s_cbranch_scc0 .LBB0_743
	s_cmpk_gt_u32 s21, 0x49f
	s_cbranch_scc0 .LBB0_744
	s_cmpk_gt_u32 s21, 0x89f
	s_cbranch_scc0 .LBB0_747
	v_readlane_b32 s56, v254, 14
	s_add_i32 s12, s21, 0xfffff760
	v_readlane_b32 s68, v254, 26
	v_readlane_b32 s69, v254, 27
	s_lshr_b32 s27, s12, 4
	s_and_b32 s28, s21, 15
	v_readlane_b32 s57, v254, 15
	v_readlane_b32 s58, v254, 16
	v_readlane_b32 s59, v254, 17
	v_readlane_b32 s60, v254, 18
	v_readlane_b32 s61, v254, 19
	v_readlane_b32 s62, v254, 20
	v_readlane_b32 s63, v254, 21
	v_readlane_b32 s64, v254, 22
	v_readlane_b32 s65, v254, 23
	v_readlane_b32 s66, v254, 24
	v_readlane_b32 s67, v254, 25
	v_readlane_b32 s70, v254, 28
	v_readlane_b32 s71, v254, 29
	s_mov_b64 s[14:15], s[68:69]
	s_cbranch_execz .LBB0_748
	s_mov_b64 s[16:17], 0x400
	s_movk_i32 s29, 0x1000
	s_mov_b64 s[12:13], s[4:5]
	s_cbranch_execz .LBB0_745
	s_branch .LBB0_746
